# grid barrier tail: generation by shift and last-arriver test by mask when per-XCD count is a power of two, set up while the arrival atomic is in flight
# baseline (speedup 1.0000x reference)
.LBB0_134:
	s_or_b64 exec, exec, s[6:7]
	s_waitcnt lgkmcnt(0)
	v_readfirstlane_b32 s5, v3
	v_readfirstlane_b32 s6, v1
	s_add_i32 s7, s5, -1
	s_and_b32 s8, s5, s7
	s_ff1_i32_b32 s9, s5
	s_waitcnt vmcnt(0)
	v_readfirstlane_b32 s4, v4
	s_cmp_lg_u32 s8, 0
	s_cbranch_scc1 .Lgb1_slow
	s_lshr_b32 s10, s4, s9
	s_add_i32 s10, s10, 1
	s_mul_i32 s12, s10, s6
	s_add_i32 s11, s4, 1
	s_and_b32 s11, s11, s7
	s_add_u32 s2, s20, 0x1a02dc00
	s_addc_u32 s3, s21, 0
	v_mov_b32_e32 v1, 0
	s_cmp_eq_u32 s11, 0
	s_cbranch_scc0 .Lgb1_poll
	s_branch .Lgb1_lead
.Lgb1_slow:
	s_mov_b32 s7, 0
	s_mov_b32 s8, s5
	s_cmp_ge_u32 s4, s8
	s_addc_u32 s7, s7, 0
	s_add_u32 s8, s8, s5
	s_cmp_ge_u32 s4, s8
	s_addc_u32 s7, s7, 0
	s_add_u32 s8, s8, s5
	s_cmp_ge_u32 s4, s8
	s_addc_u32 s7, s7, 0
	s_add_u32 s8, s8, s5
	s_cmp_ge_u32 s4, s8
	s_addc_u32 s7, s7, 0
	s_add_u32 s8, s8, s5
	s_cmp_ge_u32 s4, s8
	s_addc_u32 s7, s7, 0
	s_add_u32 s8, s8, s5
	s_cmp_ge_u32 s4, s8
	s_addc_u32 s7, s7, 0
	s_add_u32 s8, s8, s5
	s_cmp_ge_u32 s4, s8
	s_addc_u32 s7, s7, 0
	s_add_u32 s8, s8, s5
	s_cmp_ge_u32 s4, s8
	s_addc_u32 s7, s7, 0
	s_add_u32 s8, s8, s5
	s_cmp_ge_u32 s4, s8
	s_addc_u32 s7, s7, 0
	s_add_u32 s8, s8, s5
	s_cmp_ge_u32 s4, s8
	s_addc_u32 s7, s7, 0
	s_add_u32 s8, s8, s5
	s_add_i32 s9, s7, 1
	s_mul_i32 s10, s9, s5
	s_mul_i32 s12, s9, s6
	s_add_u32 s2, s20, 0x1a02dc00
	s_addc_u32 s3, s21, 0
	v_mov_b32_e32 v1, 0
	s_add_i32 s11, s4, 1
	s_cmp_eq_u32 s11, s10
	s_cbranch_scc0 .Lgb1_poll
.Lgb1_lead:
	buffer_wbl2 sc1
	s_waitcnt vmcnt(0)
	v_mov_b32_e32 v2, 1
	global_atomic_add v1, v2, s[2:3]
